# grid barrier: first local arriver of each XCD starts an early L2 writeback
# baseline (speedup 1.0000x reference)
; __device__ __forceinline__ unsigned xb_ld(unsigned* p)              { return __hip_atomic_load(p, __ATOMIC_RELAXED, __HIP_MEMORY_SCOPE_AGENT); }
; __device__ __forceinline__ unsigned xb_add(unsigned* p, unsigned v) { return __hip_atomic_fetch_add(p, v, __ATOMIC_RELAXED, __HIP_MEMORY_SCOPE_AGENT); }
; #define XB_SPIN(cond, bar) do { unsigned _sp = 0; while (cond) { __builtin_amdgcn_s_sleep(1); \
;     if ((++_sp & 255u) == 0u) { if (xb_ld(&(bar)[XB_TMO])) break; if (_sp > XB_SPIN_CAP) { atomicAdd(&(bar)[XB_TMO], 1u); break; } } } } while (0)
; __device__ __forceinline__ void xcd_barrier(const XcdBarrier& b) {
;     ...
;         unsigned nloc = b.st[0], nx = b.st[1];
;         if (nloc == 0u) { xcd_barrier_complete(bar, b.x, nloc, nx); b.st[0] = nloc; b.st[1] = nx; }
;         const unsigned old = xb_add(&bar[XB_XSUB(b.x)], 1u);
;         const unsigned gen = old / nloc;
;         if (old + 1u == (gen + 1u) * nloc) {
;             __builtin_amdgcn_fence(__ATOMIC_RELEASE, "agent");
;             asm volatile("s_waitcnt vmcnt(0)" ::: "memory");
;             const unsigned og = xb_add(&bar[XB_TOP], 1u);
;             const unsigned tg = og / nx;
;             if (og + 1u == (tg + 1u) * nx) xb_add(&bar[XB_TOPGEN], 1u);
;             else XB_SPIN(xb_ld(&bar[XB_TOPGEN]) == tg, bar);
;             __builtin_amdgcn_fence(__ATOMIC_ACQUIRE, "agent");
;             xb_add(&bar[XB_XGEN(b.x)], 1u);
;             asm volatile("s_waitcnt vmcnt(0)" ::: "memory");
;         } else {
;             XB_SPIN(xb_ld(&bar[XB_XGEN(b.x)]) == gen, bar);
;             __builtin_amdgcn_fence(__ATOMIC_ACQUIRE, "agent");
;             asm volatile("s_waitcnt vmcnt(0)" ::: "memory");
;         }
.LBB0_1567:
	s_or_b64 exec, exec, s[6:7]
	v_cvt_f32_u32_e32 v5, v3
	s_waitcnt vmcnt(0)
	v_readfirstlane_b32 s4, v4
	v_sub_u32_e32 v4, 0, v3
	v_rcp_iflag_f32_e32 v5, v5
	v_add_u32_e32 v6, s4, v0
	v_mul_f32_e32 v5, 0x4f7ffffe, v5
	v_cvt_u32_f32_e32 v5, v5
	v_mul_lo_u32 v0, v4, v5
	v_mul_hi_u32 v0, v5, v0
	v_add_u32_e32 v0, v5, v0
	v_mul_hi_u32 v0, v6, v0
	v_mul_lo_u32 v4, v0, v3
	v_sub_u32_e32 v4, v6, v4
	v_add_u32_e32 v5, 1, v0
	v_cmp_ge_u32_e32 vcc, v4, v3
	s_nop 1
	v_cndmask_b32_e32 v0, v0, v5, vcc
	v_sub_u32_e32 v5, v4, v3
	v_cndmask_b32_e32 v4, v4, v5, vcc
	v_add_u32_e32 v5, 1, v0
	v_cmp_ge_u32_e32 vcc, v4, v3
	v_add_u32_e32 v4, 1, v6
	s_nop 0
	v_cndmask_b32_e32 v0, v0, v5, vcc
	v_mul_lo_u32 v5, v3, v0
	v_add_u32_e32 v3, v5, v3
	v_cmp_ne_u32_e32 vcc, v4, v3
	s_and_saveexec_b64 s[4:5], vcc
	s_xor_b64 s[4:5], exec, s[4:5]
	s_cbranch_execz .LBB0_1581
	v_cmp_eq_u32_e32 vcc, v6, v5
	s_cbranch_vccz .Lxb_nofl
	buffer_wbl2 sc1
.Lxb_nofl:
	s_waitcnt lgkmcnt(0)
	v_mov_b32_e32 v2, 0x2000
	global_load_dword v2, v2, s[2:3] offset:1024 sc1
	s_add_u32 s8, s2, 0x2400
	s_addc_u32 s9, s3, 0
	s_waitcnt vmcnt(0)
	v_cmp_eq_u32_e32 vcc, v2, v0
	s_and_saveexec_b64 s[6:7], vcc
	s_cbranch_execz .LBB0_1580
	s_mov_b32 s20, 1
	s_mov_b64 s[10:11], 0
	s_branch .LBB0_1571
